# v139 + attention phase entry keeps only the LDS wait before its barrier (LRU stores no longer drained there)
# baseline (speedup 1.0000x reference)
.LBB0_370:
	s_cmpk_gt_i32 s2, 0x1ff
	s_waitcnt lgkmcnt(0)
	s_barrier
	s_cbranch_scc1 .LBB0_432
	s_add_u32 s17, s78, 0x6800000
	s_addc_u32 s58, s79, 0
	s_add_u32 s59, s78, 0xa800000
	s_addc_u32 s60, s79, 0
	s_add_u32 s61, s78, 0xe800000
	s_addc_u32 s62, s79, 0
	s_add_u32 s63, s78, 0x12800000
	s_addc_u32 s64, s79, 0
	s_add_u32 s65, s78, 0x200000
	s_addc_u32 s66, s79, 0
	s_ashr_i32 s0, s2, 3
	s_lshr_b32 s1, s0, 29
	s_add_i32 s1, s0, s1
	s_and_b32 s1, s1, -8
	s_sub_i32 s0, s0, s1
	s_ashr_i32 s4, s0, 31
	s_lshr_b32 s4, s4, 29
	s_add_i32 s4, s0, s4
	s_ashr_i32 s5, s4, 3
	s_and_b32 s4, s4, -8
	s_sub_i32 s0, s0, s4
	s_sub_i32 s67, 15, s0
	s_cmp_lt_i32 s0, 0
	s_cselect_b32 s10, s67, s0
	s_lshl_b32 s8, s10, 8
	s_bfe_u32 s0, s10, 0x60011
	s_or_b32 s0, s0, s8
	s_addk_i32 s0, 0xff
	s_sext_i32_i16 s0, s0
	s_and_b32 s6, s0, 0xffffffc0
	s_and_b32 s0, s2, 7
	s_or_b32 s0, s1, s0
	s_add_i32 s12, s5, s0
	s_and_b32 s7, s12, 7
	s_lshl_b32 s0, s7, 17
	s_add_u32 s11, s28, s0
	s_addc_u32 s13, s29, 0
	s_lshl_b32 s0, s12, 9
	s_and_b32 s0, s0, 0xfffff000
	s_ashr_i32 s1, s0, 31
	s_lshl_b64 s[4:5], s[0:1], 2
	s_mov_b32 s9, 0
	s_add_u32 s1, s11, s4
	s_addc_u32 s11, s13, s5
	s_lshl_b64 s[4:5], s[8:9], 2
	s_add_u32 s18, s1, s4
	s_addc_u32 s19, s11, s5
	s_ashr_i32 s13, s12, 31
	s_lshl_b64 s[4:5], s[12:13], 14
	s_add_u32 s52, s65, s4
	s_addc_u32 s53, s66, s5
	s_add_i32 s0, s0, s8
	s_ashr_i32 s1, s0, 31
	s_lshl_b64 s[0:1], s[0:1], 11
	s_add_u32 s0, s63, s0
	s_addc_u32 s1, s64, s1
	s_lshl_b32 s4, s7, 8
	s_add_u32 s50, s0, s4
	s_addc_u32 s51, s1, 0
	s_lshl_b64 s[0:1], s[12:13], 20
	s_add_u32 s54, s61, s0
	s_addc_u32 s55, s62, s1
	s_add_u32 s56, s59, s0
	s_mov_b32 s11, s9
	s_addc_u32 s57, s60, s1
	s_lshl_b64 s[4:5], s[10:11], 16
	s_add_u32 s4, s17, s4
	s_addc_u32 s5, s58, s5
	v_mov_b32_e32 v10, v254
	s_add_u32 s14, s4, s0
	s_addc_u32 s15, s5, s1
	v_readfirstlane_b32 s0, v10
	s_ashr_i32 s0, s0, 1
	s_movk_i32 s1, 0xffe0
	v_mov_b32_e32 v0, s0
	v_bfi_b32 v0, s1, v0, v10
	v_ashrrev_i32_e32 v1, 31, v0
	v_lshlrev_b64 v[0:1], 8, v[0:1]
	v_lshl_add_u64 v[2:3], s[14:15], 0, v[0:1]
	v_lshrrev_b32_e32 v0, 1, v10
	v_and_b32_e32 v0, 16, v0
	v_mov_b32_e32 v1, 0
	v_lshl_add_u64 v[2:3], v[2:3], 0, v[0:1]
	v_ashrrev_i32_e32 v11, 4, v10
	global_load_dwordx4 v[158:161], v[2:3], off
	global_load_dwordx4 v[154:157], v[2:3], off offset:32
	global_load_dwordx4 v[150:153], v[2:3], off offset:64
	global_load_dwordx4 v[146:149], v[2:3], off offset:96
	global_load_dwordx4 v[142:145], v[2:3], off offset:128
	global_load_dwordx4 v[138:141], v[2:3], off offset:160
	global_load_dwordx4 v[134:137], v[2:3], off offset:192
	global_load_dwordx4 v[130:133], v[2:3], off offset:224
	v_add_u32_e32 v2, s6, v11
	v_ashrrev_i32_e32 v3, 31, v2
	v_lshlrev_b32_e32 v12, 4, v10
	v_lshlrev_b64 v[2:3], 8, v[2:3]
	s_mov_b64 s[0:1], 0x2000
	v_and_b32_e32 v0, 0xf0, v12
	v_lshl_add_u64 v[4:5], s[54:55], 0, v[2:3]
	v_lshl_add_u64 v[6:7], v[2:3], 0, s[0:1]
	v_lshl_add_u64 v[2:3], s[56:57], 0, v[2:3]
	v_lshl_add_u64 v[2:3], v[2:3], 0, v[0:1]
	v_lshl_add_u64 v[8:9], s[56:57], 0, v[6:7]
	v_lshl_add_u64 v[8:9], v[8:9], 0, v[0:1]
	global_load_dwordx4 v[106:109], v[2:3], off
	global_load_dwordx4 v[110:113], v[8:9], off
	v_lshl_add_u64 v[2:3], v[4:5], 0, v[0:1]
	v_lshl_add_u64 v[4:5], s[54:55], 0, v[6:7]
	v_lshl_add_u64 v[4:5], v[4:5], 0, v[0:1]
	global_load_dwordx4 v[98:101], v[2:3], off
	global_load_dwordx4 v[102:105], v[4:5], off
	v_mbcnt_lo_u32_b32 v0, -1, 0
	s_movk_i32 s0, 0xf0
	v_mbcnt_hi_u32_b32 v204, -1, v0
	v_and_b32_e32 v0, 0xf0, v10
	s_waitcnt vmcnt(0)
	v_lshlrev_b32_e32 v2, 8, v11
	v_bitop3_b32 v0, v12, v0, s0 bitop3:0x6c
	s_movk_i32 s11, 0x1000
	s_movk_i32 s68, 0xefff
	s_mov_b32 s69, 0x41000000
	s_mov_b32 s16, 0x3e0293ee
	s_movk_i32 s72, 0xf800
	v_mov_b32_e32 v202, 0xff800000
	v_mov_b32_e32 v192, 0xf149f2ca
	v_add3_u32 v0, 0, v2, v0
	s_mov_b32 s73, s2
	s_waitcnt vmcnt(3)
	ds_write_b128 v0, v[106:109] offset:32768
	s_waitcnt vmcnt(2)
	ds_write_b128 v0, v[110:113] offset:40960
	s_waitcnt lgkmcnt(0)
	s_barrier
	s_branch .LBB0_373
